# P2 q/k epilogue: head-norm cross-row sums via v_permlane16/32_swap instead of ds_bpermute round trips
# baseline (speedup 1.0000x reference)
; __device__ __forceinline__ unsigned cvt_pk_bf16(float lo, float hi) { unsigned r; asm volatile("v_cvt_pk_bf16_f32 %0, %1, %2" : "=v"(r) : "v"(lo), "v"(hi)); return r; }
;     __device__ __forceinline__ void operator()(const f32x4 (&acc)[2][2][4][2], const Unit& u, int wr, int wc, int fr, int fq) const {
;     ...
;                         for (int n = 0; n < 2; ++n) { const f32x4 x = acc[ai][bj][m][n]; ss += (x[0] * x[0] + x[1] * x[1]) + (x[2] * x[2] + x[3] * x[3]); }
;                     ss += __shfl_xor(ss, 16); ss += __shfl_xor(ss, 32);
;                     const float rstd = __builtin_amdgcn_rsqf(ss * (1.0f / 64.0f) + eps);
;                     bf16_t* rowp = dst + (row0 + ai * HALF + m * 16) * 512 + colb;
; #pragma unroll
;                     for (int bj = 0; bj < 2; ++bj) { const f32x4 v0 = acc[ai][bj][m][0] * rstd * gv[bj][0], v1 = acc[ai][bj][m][1] * rstd * gv[bj][1];
;                         u32x4 w; w.x = cvt_pk_bf16(v0[0], v0[1]); w.y = cvt_pk_bf16(v0[2], v0[3]); w.z = cvt_pk_bf16(v1[0], v1[1]); w.w = cvt_pk_bf16(v1[2], v1[3]);
;                         *(u32x4*)(rowp + 32 * bj) = w; }
.LBB0_281:
	s_lshl_b32 s31, s40, 8
	s_cmp_lt_i32 s40, 2
	s_cselect_b64 vcc, -1, 0
	s_and_b64 s[6:7], vcc, exec
	s_cselect_b32 s7, s9, s11
	s_cselect_b32 s6, s8, s10
	global_load_dwordx4 v[156:159], v179, s[6:7]
	global_load_dwordx4 v[160:163], v179, s[6:7] offset:16
	global_load_dwordx4 v[182:185], v179, s[6:7] offset:128
	global_load_dwordx4 v[186:189], v179, s[6:7] offset:144
	v_pk_mul_f32 v[154:155], v[128:129], v[128:129]
	v_pk_mul_f32 v[192:193], v[126:127], v[126:127]
	v_pk_mul_f32 v[194:195], v[124:125], v[124:125]
	v_pk_mul_f32 v[196:197], v[122:123], v[122:123]
	v_pk_mov_b32 v[208:209], v[192:193], v[154:155] op_sel:[1,0]
	v_mov_b32_e32 v193, v155
	v_pk_mov_b32 v[154:155], v[196:197], v[194:195] op_sel:[1,0]
	v_mov_b32_e32 v197, v195
	v_mul_f32_e32 v138, v119, v119
	v_mul_f32_e32 v198, v121, v121
	v_pk_add_f32 v[192:193], v[208:209], v[192:193]
	v_pk_add_f32 v[154:155], v[154:155], v[196:197]
	v_mul_f32_e32 v191, v106, v106
	v_mul_f32_e32 v212, v107, v107
	v_mul_f32_e32 v213, v108, v108
	v_mul_f32_e32 v214, v109, v109
	v_pk_fma_f32 v[194:195], v[118:119], v[118:119], v[138:139] op_sel_hi:[1,1,0]
	v_pk_fma_f32 v[198:199], v[120:121], v[120:121], v[198:199] op_sel_hi:[1,1,0]
	v_pk_add_f32 v[192:193], v[192:193], v[192:193] op_sel:[0,1] op_sel_hi:[1,0]
	v_pk_add_f32 v[154:155], v[154:155], v[154:155] op_sel:[0,1] op_sel_hi:[1,0]
	v_mov_b32_e32 v195, v213
	v_mov_b32_e32 v199, v214
	v_mov_b32_e32 v193, v191
	v_mov_b32_e32 v155, v212
	v_pk_add_f32 v[194:195], v[194:195], v[198:199]
	v_pk_add_f32 v[154:155], v[192:193], v[154:155]
	s_cselect_b32 s6, s76, 0x8000000
	v_pk_add_f32 v[154:155], v[154:155], v[194:195]
	s_add_u32 s6, s12, s6
	v_add_f32_e32 v138, v154, v155
	v_mov_b32_e32 v154, v138
	v_mov_b32_e32 v244, v138
	s_addc_u32 s7, s13, 0
	s_and_b32 s31, s31, 0x100
	v_or_b32_e32 v155, s31, v175
	v_pk_mul_f32 v[200:201], v[116:117], v[116:117]
	s_nop 1
	v_permlane16_swap_b32_e32 v154, v244
	v_add_f32_e32 v138, v244, v154
	v_mov_b32_e32 v154, v138
	v_mov_b32_e32 v244, v138
	v_pk_mul_f32 v[202:203], v[114:115], v[114:115]
	v_pk_mul_f32 v[204:205], v[112:113], v[112:113]
	v_pk_mul_f32 v[206:207], v[110:111], v[110:111]
	v_cndmask_b32_e32 v190, 1.0, v181, vcc
	s_nop 1
	v_permlane32_swap_b32_e32 v154, v244
	v_add_f32_e32 v138, v244, v154
	v_fmamk_f32 v138, v138, 0x3c800000, v180
	v_rsq_f32_e32 v196, v138
	v_lshlrev_b32_e32 v138, 1, v155
	v_lshlrev_b64 v[152:153], 10, v[152:153]
	v_pk_mov_b32 v[210:211], v[202:203], v[200:201] op_sel:[1,0]
	v_mov_b32_e32 v203, v201
	v_pk_mov_b32 v[200:201], v[206:207], v[204:205] op_sel:[1,0]
	v_mov_b32_e32 v207, v205
	v_lshl_add_u64 v[154:155], s[6:7], 0, v[138:139]
	v_pk_add_f32 v[194:195], v[200:201], v[206:207]
	v_lshl_add_u64 v[152:153], v[154:155], 0, v[152:153]
	v_pk_mul_f32 v[198:199], v[126:127], v[196:197] op_sel_hi:[1,0]
	v_pk_mul_f32 v[200:201], v[128:129], v[196:197] op_sel_hi:[1,0]
	v_pk_add_f32 v[192:193], v[210:211], v[202:203]
	v_pk_mul_f32 v[202:203], v[122:123], v[196:197] op_sel_hi:[1,0]
	v_pk_mul_f32 v[204:205], v[124:125], v[196:197] op_sel_hi:[1,0]
	v_mul_f32_e32 v215, v90, v90
	v_mul_f32_e32 v216, v91, v91
	v_mul_f32_e32 v138, v103, v103
	v_pk_mul_f32 v[206:207], v[118:119], v[196:197] op_sel_hi:[1,0]
	v_pk_mul_f32 v[208:209], v[120:121], v[196:197] op_sel_hi:[1,0]
	v_pk_mul_f32 v[106:107], v[106:107], v[196:197] op_sel_hi:[1,0]
	v_pk_mul_f32 v[108:109], v[108:109], v[196:197] op_sel_hi:[1,0]
	s_waitcnt vmcnt(0)
	v_pk_mul_f32 v[154:155], v[190:191], v[158:159] op_sel_hi:[0,1]
	v_pk_mul_f32 v[156:157], v[190:191], v[156:157] op_sel_hi:[0,1]
	v_pk_mul_f32 v[126:127], v[190:191], v[162:163] op_sel_hi:[0,1]
	v_pk_mul_f32 v[128:129], v[190:191], v[160:161] op_sel_hi:[0,1]
	v_pk_mul_f32 v[160:161], v[154:155], v[200:201]
	v_pk_mul_f32 v[158:159], v[156:157], v[198:199]
	v_pk_mul_f32 v[124:125], v[190:191], v[182:183] op_sel_hi:[0,1]
	v_pk_mul_f32 v[162:163], v[126:127], v[204:205]
	v_pk_mul_f32 v[182:183], v[128:129], v[202:203]
	v_cvt_pk_bf16_f32 v158, v158, v159
	v_cvt_pk_bf16_f32 v159, v160, v161
	v_pk_mul_f32 v[118:119], v[190:191], v[188:189] op_sel_hi:[0,1]
	v_cvt_pk_bf16_f32 v160, v182, v183
	v_cvt_pk_bf16_f32 v161, v162, v163
	global_store_dwordx4 v[152:153], v[158:161], off
	v_mul_f32_e32 v162, v92, v92
	v_mul_f32_e32 v182, v93, v93
	v_pk_add_f32 v[158:159], v[192:193], v[192:193] op_sel:[0,1] op_sel_hi:[1,0]
	v_pk_add_f32 v[160:161], v[194:195], v[194:195] op_sel:[0,1] op_sel_hi:[1,0]
	v_mov_b32_e32 v159, v215
	v_mov_b32_e32 v161, v216
	v_pk_add_f32 v[158:159], v[158:159], v[160:161]
	v_pk_fma_f32 v[160:161], v[102:103], v[102:103], v[138:139] op_sel_hi:[1,1,0]
	v_mul_f32_e32 v138, v105, v105
	v_mov_b32_e32 v161, v162
	v_pk_fma_f32 v[162:163], v[104:105], v[104:105], v[138:139] op_sel_hi:[1,1,0]
	v_pk_mul_f32 v[120:121], v[190:191], v[186:187] op_sel_hi:[0,1]
	v_mov_b32_e32 v163, v182
	v_pk_add_f32 v[160:161], v[160:161], v[162:163]
	v_pk_mul_f32 v[122:123], v[190:191], v[184:185] op_sel_hi:[0,1]
	v_pk_add_f32 v[158:159], v[158:159], v[160:161]
	v_pk_mul_f32 v[160:161], v[124:125], v[206:207]
	v_add_f32_e32 v138, v158, v159
	v_mov_b32_e32 v162, v138
	v_mov_b32_e32 v244, v138
	v_pk_mul_f32 v[158:159], v[122:123], v[208:209]
	s_nop 1
	v_permlane16_swap_b32_e32 v162, v244
	v_add_f32_e32 v138, v244, v162
	v_mov_b32_e32 v182, v138
	v_mov_b32_e32 v244, v138
	v_pk_mul_f32 v[162:163], v[118:119], v[108:109]
	v_pk_mul_f32 v[108:109], v[120:121], v[106:107]
	v_cvt_pk_bf16_f32 v106, v160, v161
	v_cvt_pk_bf16_f32 v107, v158, v159
	s_nop 1
	v_permlane32_swap_b32_e32 v182, v244
	v_add_f32_e32 v138, v244, v182
	v_fmamk_f32 v138, v138, 0x3c800000, v180
	v_rsq_f32_e32 v138, v138
; __device__ __forceinline__ unsigned cvt_pk_bf16(float lo, float hi) { unsigned r; asm volatile("v_cvt_pk_bf16_f32 %0, %1, %2" : "=v"(r) : "v"(lo), "v"(hi)); return r; }
;     __device__ __forceinline__ void operator()(const f32x4 (&acc)[2][2][4][2], const Unit& u, int wr, int wc, int fr, int fq) const {
;     ...
;                         for (int n = 0; n < 2; ++n) { const f32x4 x = acc[ai][bj][m][n]; ss += (x[0] * x[0] + x[1] * x[1]) + (x[2] * x[2] + x[3] * x[3]); }
;                     ss += __shfl_xor(ss, 16); ss += __shfl_xor(ss, 32);
;                     const float rstd = __builtin_amdgcn_rsqf(ss * (1.0f / 64.0f) + eps);
;                     bf16_t* rowp = dst + (row0 + ai * HALF + m * 16) * 512 + colb;
; #pragma unroll
;                     for (int bj = 0; bj < 2; ++bj) { const f32x4 v0 = acc[ai][bj][m][0] * rstd * gv[bj][0], v1 = acc[ai][bj][m][1] * rstd * gv[bj][1];
;                         u32x4 w; w.x = cvt_pk_bf16(v0[0], v0[1]); w.y = cvt_pk_bf16(v0[2], v0[3]); w.z = cvt_pk_bf16(v1[0], v1[1]); w.w = cvt_pk_bf16(v1[2], v1[3]);
;                         *(u32x4*)(rowp + 32 * bj) = w; }
	v_cvt_pk_bf16_f32 v108, v108, v109
	v_cvt_pk_bf16_f32 v109, v162, v163
	global_store_dwordx4 v[152:153], v[106:109], off offset:64
	v_pk_mul_f32 v[110:111], v[110:111], v[138:139] op_sel_hi:[1,0]
	v_pk_mul_f32 v[112:113], v[112:113], v[138:139] op_sel_hi:[1,0]
	v_pk_mul_f32 v[106:107], v[114:115], v[138:139] op_sel_hi:[1,0]
	v_pk_mul_f32 v[108:109], v[116:117], v[138:139] op_sel_hi:[1,0]
	v_pk_mul_f32 v[106:107], v[156:157], v[106:107]
	v_pk_mul_f32 v[108:109], v[154:155], v[108:109]
	v_pk_mul_f32 v[110:111], v[128:129], v[110:111]
	v_cvt_pk_bf16_f32 v106, v106, v107
	v_cvt_pk_bf16_f32 v107, v108, v109
	v_pk_mul_f32 v[112:113], v[126:127], v[112:113]
	v_cvt_pk_bf16_f32 v108, v110, v111
	v_add_co_u32_e32 v110, vcc, s56, v152
	v_cvt_pk_bf16_f32 v109, v112, v113
	v_pk_mul_f32 v[102:103], v[102:103], v[138:139] op_sel_hi:[1,0]
	s_nop 0
	v_addc_co_u32_e32 v111, vcc, 0, v153, vcc
	global_store_dwordx4 v[110:111], v[106:109], off
	v_pk_mul_f32 v[102:103], v[124:125], v[102:103]
	v_pk_mul_f32 v[90:91], v[90:91], v[138:139] op_sel_hi:[1,0]
	v_pk_mul_f32 v[106:107], v[100:101], v[100:101]
	v_pk_mul_f32 v[108:109], v[98:99], v[98:99]
	v_pk_mul_f32 v[92:93], v[92:93], v[138:139] op_sel_hi:[1,0]
	v_pk_mov_b32 v[112:113], v[108:109], v[106:107] op_sel:[1,0]
	v_mov_b32_e32 v109, v107
	v_pk_add_f32 v[106:107], v[112:113], v[108:109]
	v_pk_mul_f32 v[108:109], v[96:97], v[96:97]
	v_pk_mul_f32 v[112:113], v[94:95], v[94:95]
	v_pk_add_f32 v[106:107], v[106:107], v[106:107] op_sel:[0,1] op_sel_hi:[1,0]
	v_pk_mov_b32 v[114:115], v[112:113], v[108:109] op_sel:[1,0]
	v_mov_b32_e32 v113, v109
	v_pk_add_f32 v[108:109], v[114:115], v[112:113]
	v_mul_f32_e32 v112, v74, v74
	v_mul_f32_e32 v113, v75, v75
	v_pk_add_f32 v[108:109], v[108:109], v[108:109] op_sel:[0,1] op_sel_hi:[1,0]
	v_mov_b32_e32 v107, v112
	v_mov_b32_e32 v109, v113
	v_pk_add_f32 v[106:107], v[106:107], v[108:109]
	v_mul_f32_e32 v108, v87, v87
	v_mul_f32_e32 v112, v89, v89
	v_mul_f32_e32 v114, v76, v76
	v_mul_f32_e32 v115, v77, v77
	v_pk_fma_f32 v[108:109], v[86:87], v[86:87], v[108:109] op_sel_hi:[1,1,0]
	v_pk_fma_f32 v[112:113], v[88:89], v[88:89], v[112:113] op_sel_hi:[1,1,0]
	v_mov_b32_e32 v109, v114
	v_mov_b32_e32 v113, v115
	v_pk_add_f32 v[108:109], v[108:109], v[112:113]
	v_pk_mul_f32 v[104:105], v[104:105], v[138:139] op_sel_hi:[1,0]
	v_pk_add_f32 v[106:107], v[106:107], v[108:109]
	v_pk_mul_f32 v[104:105], v[122:123], v[104:105]
	v_add_f32_e32 v106, v106, v107
	v_mov_b32_e32 v107, v106
	v_mov_b32_e32 v244, v106
	s_nop 1
	v_permlane16_swap_b32_e32 v107, v244
	v_add_f32_e32 v108, v244, v107
	v_mov_b32_e32 v109, v108
	v_mov_b32_e32 v244, v108
	v_pk_mul_f32 v[106:107], v[118:119], v[92:93]
	v_pk_mul_f32 v[92:93], v[120:121], v[90:91]
	v_cvt_pk_bf16_f32 v90, v102, v103
	v_cvt_pk_bf16_f32 v91, v104, v105
	s_nop 1
	v_permlane32_swap_b32_e32 v109, v244
	v_add_f32_e32 v102, v244, v109
	v_fmamk_f32 v102, v102, 0x3c800000, v180
	v_rsq_f32_e32 v102, v102
	v_cvt_pk_bf16_f32 v92, v92, v93
	v_cvt_pk_bf16_f32 v93, v106, v107
	global_store_dwordx4 v[110:111], v[90:93], off offset:64
	v_pk_mul_f32 v[94:95], v[94:95], v[102:103] op_sel_hi:[1,0]
	v_pk_mul_f32 v[96:97], v[96:97], v[102:103] op_sel_hi:[1,0]
	v_pk_mul_f32 v[90:91], v[98:99], v[102:103] op_sel_hi:[1,0]
	v_pk_mul_f32 v[92:93], v[100:101], v[102:103] op_sel_hi:[1,0]
	v_pk_mul_f32 v[90:91], v[156:157], v[90:91]
	v_pk_mul_f32 v[92:93], v[154:155], v[92:93]
	v_pk_mul_f32 v[94:95], v[128:129], v[94:95]
	v_cvt_pk_bf16_f32 v90, v90, v91
	v_cvt_pk_bf16_f32 v91, v92, v93
	v_pk_mul_f32 v[96:97], v[126:127], v[96:97]
	v_cvt_pk_bf16_f32 v92, v94, v95
	v_add_co_u32_e32 v94, vcc, s60, v152
	v_cvt_pk_bf16_f32 v93, v96, v97
	v_pk_mul_f32 v[86:87], v[86:87], v[102:103] op_sel_hi:[1,0]
	s_nop 0
	v_addc_co_u32_e32 v95, vcc, 0, v153, vcc
	global_store_dwordx4 v[94:95], v[90:93], off
	v_pk_mul_f32 v[86:87], v[124:125], v[86:87]
	v_pk_mul_f32 v[74:75], v[74:75], v[102:103] op_sel_hi:[1,0]
	v_pk_mul_f32 v[90:91], v[84:85], v[84:85]
	v_pk_mul_f32 v[92:93], v[82:83], v[82:83]
	v_pk_mul_f32 v[76:77], v[76:77], v[102:103] op_sel_hi:[1,0]
	v_pk_mov_b32 v[96:97], v[92:93], v[90:91] op_sel:[1,0]
	v_mov_b32_e32 v93, v91
	v_pk_add_f32 v[90:91], v[96:97], v[92:93]
	v_pk_mul_f32 v[92:93], v[80:81], v[80:81]
	v_pk_mul_f32 v[96:97], v[78:79], v[78:79]
	v_pk_add_f32 v[90:91], v[90:91], v[90:91] op_sel:[0,1] op_sel_hi:[1,0]
	v_pk_mov_b32 v[98:99], v[96:97], v[92:93] op_sel:[1,0]
	v_mov_b32_e32 v97, v93
	v_pk_add_f32 v[92:93], v[98:99], v[96:97]
	v_mul_f32_e32 v96, v66, v66
	v_mul_f32_e32 v97, v67, v67
	v_pk_add_f32 v[92:93], v[92:93], v[92:93] op_sel:[0,1] op_sel_hi:[1,0]
	v_mov_b32_e32 v91, v96
	v_mov_b32_e32 v93, v97
	v_pk_add_f32 v[90:91], v[90:91], v[92:93]
	v_mul_f32_e32 v92, v71, v71
	v_mul_f32_e32 v96, v73, v73
	v_mul_f32_e32 v98, v68, v68
	v_mul_f32_e32 v99, v69, v69
	v_pk_fma_f32 v[92:93], v[70:71], v[70:71], v[92:93] op_sel_hi:[1,1,0]
	v_pk_fma_f32 v[96:97], v[72:73], v[72:73], v[96:97] op_sel_hi:[1,1,0]
	v_mov_b32_e32 v93, v98
	v_mov_b32_e32 v97, v99
	v_pk_add_f32 v[92:93], v[92:93], v[96:97]
	v_pk_mul_f32 v[88:89], v[88:89], v[102:103] op_sel_hi:[1,0]
	v_pk_add_f32 v[90:91], v[90:91], v[92:93]
	v_pk_mul_f32 v[88:89], v[122:123], v[88:89]
	v_add_f32_e32 v90, v90, v91
	v_mov_b32_e32 v91, v90
	v_mov_b32_e32 v244, v90
	s_nop 1
	v_permlane16_swap_b32_e32 v91, v244
	v_add_f32_e32 v92, v244, v91
	v_mov_b32_e32 v93, v92
	v_mov_b32_e32 v244, v92
	v_pk_mul_f32 v[90:91], v[118:119], v[76:77]
	v_pk_mul_f32 v[76:77], v[120:121], v[74:75]
	v_cvt_pk_bf16_f32 v74, v86, v87
	v_cvt_pk_bf16_f32 v75, v88, v89
	s_nop 1
	v_permlane32_swap_b32_e32 v93, v244
	v_add_f32_e32 v86, v244, v93
; __device__ __forceinline__ unsigned cvt_pk_bf16(float lo, float hi) { unsigned r; asm volatile("v_cvt_pk_bf16_f32 %0, %1, %2" : "=v"(r) : "v"(lo), "v"(hi)); return r; }
;     __device__ __forceinline__ void operator()(const f32x4 (&acc)[2][2][4][2], const Unit& u, int wr, int wc, int fr, int fq) const {
;     ...
;                         for (int n = 0; n < 2; ++n) { const f32x4 x = acc[ai][bj][m][n]; ss += (x[0] * x[0] + x[1] * x[1]) + (x[2] * x[2] + x[3] * x[3]); }
;                     ss += __shfl_xor(ss, 16); ss += __shfl_xor(ss, 32);
;                     const float rstd = __builtin_amdgcn_rsqf(ss * (1.0f / 64.0f) + eps);
;                     bf16_t* rowp = dst + (row0 + ai * HALF + m * 16) * 512 + colb;
; #pragma unroll
;                     for (int bj = 0; bj < 2; ++bj) { const f32x4 v0 = acc[ai][bj][m][0] * rstd * gv[bj][0], v1 = acc[ai][bj][m][1] * rstd * gv[bj][1];
;                         u32x4 w; w.x = cvt_pk_bf16(v0[0], v0[1]); w.y = cvt_pk_bf16(v0[2], v0[3]); w.z = cvt_pk_bf16(v1[0], v1[1]); w.w = cvt_pk_bf16(v1[2], v1[3]);
;                         *(u32x4*)(rowp + 32 * bj) = w; }
	v_fmamk_f32 v86, v86, 0x3c800000, v180
	v_rsq_f32_e32 v86, v86
	v_cvt_pk_bf16_f32 v76, v76, v77
	v_cvt_pk_bf16_f32 v77, v90, v91
	global_store_dwordx4 v[94:95], v[74:77], off offset:64
	v_pk_mul_f32 v[78:79], v[78:79], v[86:87] op_sel_hi:[1,0]
	v_pk_mul_f32 v[80:81], v[80:81], v[86:87] op_sel_hi:[1,0]
	v_pk_mul_f32 v[74:75], v[82:83], v[86:87] op_sel_hi:[1,0]
	v_pk_mul_f32 v[76:77], v[84:85], v[86:87] op_sel_hi:[1,0]
	v_pk_mul_f32 v[74:75], v[156:157], v[74:75]
	v_pk_mul_f32 v[76:77], v[154:155], v[76:77]
	v_pk_mul_f32 v[78:79], v[128:129], v[78:79]
	v_cvt_pk_bf16_f32 v74, v74, v75
	v_cvt_pk_bf16_f32 v75, v76, v77
	v_pk_mul_f32 v[80:81], v[126:127], v[80:81]
	v_cvt_pk_bf16_f32 v76, v78, v79
	v_add_co_u32_e32 v78, vcc, s66, v152
	v_cvt_pk_bf16_f32 v77, v80, v81
	v_pk_mul_f32 v[70:71], v[70:71], v[86:87] op_sel_hi:[1,0]
	s_nop 0
	v_addc_co_u32_e32 v79, vcc, 0, v153, vcc
	global_store_dwordx4 v[78:79], v[74:77], off
	v_pk_mul_f32 v[70:71], v[124:125], v[70:71]
	v_pk_mul_f32 v[66:67], v[66:67], v[86:87] op_sel_hi:[1,0]
	v_pk_mul_f32 v[74:75], v[64:65], v[64:65]
	v_pk_mul_f32 v[76:77], v[62:63], v[62:63]
	v_pk_mul_f32 v[68:69], v[68:69], v[86:87] op_sel_hi:[1,0]
	v_pk_mov_b32 v[80:81], v[76:77], v[74:75] op_sel:[1,0]
	v_mov_b32_e32 v77, v75
	v_pk_add_f32 v[74:75], v[80:81], v[76:77]
	v_pk_mul_f32 v[76:77], v[60:61], v[60:61]
	v_pk_mul_f32 v[80:81], v[58:59], v[58:59]
	v_pk_add_f32 v[74:75], v[74:75], v[74:75] op_sel:[0,1] op_sel_hi:[1,0]
	v_pk_mov_b32 v[82:83], v[80:81], v[76:77] op_sel:[1,0]
	v_mov_b32_e32 v81, v77
	v_pk_add_f32 v[76:77], v[82:83], v[80:81]
	v_mul_f32_e32 v80, v42, v42
	v_mul_f32_e32 v81, v43, v43
	v_pk_add_f32 v[76:77], v[76:77], v[76:77] op_sel:[0,1] op_sel_hi:[1,0]
	v_mov_b32_e32 v75, v80
	v_mov_b32_e32 v77, v81
	v_pk_add_f32 v[74:75], v[74:75], v[76:77]
	v_mul_f32_e32 v76, v55, v55
	v_mul_f32_e32 v80, v57, v57
	v_mul_f32_e32 v82, v44, v44
	v_mul_f32_e32 v83, v45, v45
	v_pk_fma_f32 v[76:77], v[54:55], v[54:55], v[76:77] op_sel_hi:[1,1,0]
	v_pk_fma_f32 v[80:81], v[56:57], v[56:57], v[80:81] op_sel_hi:[1,1,0]
	v_mov_b32_e32 v77, v82
	v_mov_b32_e32 v81, v83
	v_pk_add_f32 v[76:77], v[76:77], v[80:81]
	v_pk_mul_f32 v[72:73], v[72:73], v[86:87] op_sel_hi:[1,0]
	v_pk_add_f32 v[74:75], v[74:75], v[76:77]
	v_pk_mul_f32 v[72:73], v[122:123], v[72:73]
	v_add_f32_e32 v74, v74, v75
	v_mov_b32_e32 v75, v74
	v_mov_b32_e32 v244, v74
	s_nop 1
	v_permlane16_swap_b32_e32 v75, v244
	v_add_f32_e32 v76, v244, v75
	v_mov_b32_e32 v77, v76
	v_mov_b32_e32 v244, v76
	v_pk_mul_f32 v[74:75], v[118:119], v[68:69]
	v_pk_mul_f32 v[68:69], v[120:121], v[66:67]
	v_cvt_pk_bf16_f32 v66, v70, v71
	v_cvt_pk_bf16_f32 v67, v72, v73
	s_nop 1
	v_permlane32_swap_b32_e32 v77, v244
	v_add_f32_e32 v70, v244, v77
	v_fmamk_f32 v70, v70, 0x3c800000, v180
	v_rsq_f32_e32 v70, v70
	v_cvt_pk_bf16_f32 v68, v68, v69
	v_cvt_pk_bf16_f32 v69, v74, v75
	global_store_dwordx4 v[78:79], v[66:69], off offset:64
	v_pk_mul_f32 v[62:63], v[62:63], v[70:71] op_sel_hi:[1,0]
	v_pk_mul_f32 v[58:59], v[58:59], v[70:71] op_sel_hi:[1,0]
	v_pk_mul_f32 v[62:63], v[156:157], v[62:63]
	v_pk_mul_f32 v[60:61], v[60:61], v[70:71] op_sel_hi:[1,0]
	v_pk_mul_f32 v[64:65], v[64:65], v[70:71] op_sel_hi:[1,0]
	v_pk_mul_f32 v[66:67], v[126:127], v[60:61]
	v_pk_mul_f32 v[60:61], v[128:129], v[58:59]
	v_cvt_pk_bf16_f32 v58, v62, v63
	v_add_co_u32_e32 v62, vcc, s69, v152
	v_pk_mul_f32 v[64:65], v[154:155], v[64:65]
	s_nop 0
	v_addc_co_u32_e32 v63, vcc, 0, v153, vcc
	v_cvt_pk_bf16_f32 v59, v64, v65
	v_cvt_pk_bf16_f32 v60, v60, v61
	v_cvt_pk_bf16_f32 v61, v66, v67
	global_store_dwordx4 v[62:63], v[58:61], off
	v_pk_mul_f32 v[54:55], v[54:55], v[70:71] op_sel_hi:[1,0]
	v_pk_mul_f32 v[42:43], v[42:43], v[70:71] op_sel_hi:[1,0]
	v_pk_mul_f32 v[58:59], v[52:53], v[52:53]
	v_pk_mul_f32 v[60:61], v[50:51], v[50:51]
	v_pk_mul_f32 v[54:55], v[124:125], v[54:55]
	v_pk_mov_b32 v[64:65], v[60:61], v[58:59] op_sel:[1,0]
	v_mov_b32_e32 v61, v59
	v_pk_add_f32 v[58:59], v[64:65], v[60:61]
	v_pk_mul_f32 v[60:61], v[48:49], v[48:49]
	v_pk_mul_f32 v[64:65], v[46:47], v[46:47]
	v_pk_add_f32 v[58:59], v[58:59], v[58:59] op_sel:[0,1] op_sel_hi:[1,0]
	v_pk_mov_b32 v[66:67], v[64:65], v[60:61] op_sel:[1,0]
	v_mov_b32_e32 v65, v61
	v_pk_add_f32 v[60:61], v[66:67], v[64:65]
	v_mul_f32_e32 v64, v26, v26
	v_mul_f32_e32 v65, v27, v27
	v_pk_add_f32 v[60:61], v[60:61], v[60:61] op_sel:[0,1] op_sel_hi:[1,0]
	v_mov_b32_e32 v59, v64
	v_mov_b32_e32 v61, v65
	v_pk_add_f32 v[58:59], v[58:59], v[60:61]
	v_mul_f32_e32 v60, v39, v39
	v_mul_f32_e32 v64, v41, v41
	v_mul_f32_e32 v66, v28, v28
	v_mul_f32_e32 v67, v29, v29
	v_pk_fma_f32 v[60:61], v[38:39], v[38:39], v[60:61] op_sel_hi:[1,1,0]
	v_pk_fma_f32 v[64:65], v[40:41], v[40:41], v[64:65] op_sel_hi:[1,1,0]
	v_mov_b32_e32 v61, v66
	v_mov_b32_e32 v65, v67
	v_pk_add_f32 v[60:61], v[60:61], v[64:65]
	v_pk_mul_f32 v[44:45], v[44:45], v[70:71] op_sel_hi:[1,0]
	v_pk_add_f32 v[58:59], v[58:59], v[60:61]
	v_pk_mul_f32 v[56:57], v[56:57], v[70:71] op_sel_hi:[1,0]
	v_add_f32_e32 v58, v58, v59
	v_mov_b32_e32 v59, v58
	v_mov_b32_e32 v244, v58
	v_pk_mul_f32 v[56:57], v[122:123], v[56:57]
	s_nop 1
	v_permlane16_swap_b32_e32 v59, v244
	v_add_f32_e32 v60, v244, v59
	v_mov_b32_e32 v61, v60
	v_mov_b32_e32 v244, v60
	v_pk_mul_f32 v[58:59], v[118:119], v[44:45]
	v_pk_mul_f32 v[44:45], v[120:121], v[42:43]
	v_cvt_pk_bf16_f32 v42, v54, v55
	v_cvt_pk_bf16_f32 v43, v56, v57
	s_nop 1
	v_permlane32_swap_b32_e32 v61, v244
	v_add_f32_e32 v54, v244, v61
	v_fmamk_f32 v54, v54, 0x3c800000, v180
	v_rsq_f32_e32 v54, v54
	v_cvt_pk_bf16_f32 v44, v44, v45
	v_cvt_pk_bf16_f32 v45, v58, v59
	global_store_dwordx4 v[62:63], v[42:45], off offset:64
; __device__ __forceinline__ unsigned cvt_pk_bf16(float lo, float hi) { unsigned r; asm volatile("v_cvt_pk_bf16_f32 %0, %1, %2" : "=v"(r) : "v"(lo), "v"(hi)); return r; }
;     __device__ __forceinline__ void operator()(const f32x4 (&acc)[2][2][4][2], const Unit& u, int wr, int wc, int fr, int fq) const {
;     ...
;                         for (int n = 0; n < 2; ++n) { const f32x4 x = acc[ai][bj][m][n]; ss += (x[0] * x[0] + x[1] * x[1]) + (x[2] * x[2] + x[3] * x[3]); }
;                     ss += __shfl_xor(ss, 16); ss += __shfl_xor(ss, 32);
;                     const float rstd = __builtin_amdgcn_rsqf(ss * (1.0f / 64.0f) + eps);
;                     bf16_t* rowp = dst + (row0 + ai * HALF + m * 16) * 512 + colb;
; #pragma unroll
;                     for (int bj = 0; bj < 2; ++bj) { const f32x4 v0 = acc[ai][bj][m][0] * rstd * gv[bj][0], v1 = acc[ai][bj][m][1] * rstd * gv[bj][1];
;                         u32x4 w; w.x = cvt_pk_bf16(v0[0], v0[1]); w.y = cvt_pk_bf16(v0[2], v0[3]); w.z = cvt_pk_bf16(v1[0], v1[1]); w.w = cvt_pk_bf16(v1[2], v1[3]);
;                         *(u32x4*)(rowp + 32 * bj) = w; }
	v_pk_mul_f32 v[46:47], v[46:47], v[54:55] op_sel_hi:[1,0]
	v_pk_mul_f32 v[48:49], v[48:49], v[54:55] op_sel_hi:[1,0]
	v_pk_mul_f32 v[42:43], v[50:51], v[54:55] op_sel_hi:[1,0]
	v_pk_mul_f32 v[44:45], v[52:53], v[54:55] op_sel_hi:[1,0]
	v_pk_mul_f32 v[42:43], v[156:157], v[42:43]
	v_pk_mul_f32 v[44:45], v[154:155], v[44:45]
	v_pk_mul_f32 v[46:47], v[128:129], v[46:47]
	v_cvt_pk_bf16_f32 v42, v42, v43
	v_cvt_pk_bf16_f32 v43, v44, v45
	v_pk_mul_f32 v[48:49], v[126:127], v[48:49]
	v_cvt_pk_bf16_f32 v44, v46, v47
	v_add_co_u32_e32 v46, vcc, s70, v152
	v_cvt_pk_bf16_f32 v45, v48, v49
	v_pk_mul_f32 v[38:39], v[38:39], v[54:55] op_sel_hi:[1,0]
	s_nop 0
	v_addc_co_u32_e32 v47, vcc, 0, v153, vcc
	global_store_dwordx4 v[46:47], v[42:45], off
	v_pk_mul_f32 v[38:39], v[124:125], v[38:39]
	v_pk_mul_f32 v[26:27], v[26:27], v[54:55] op_sel_hi:[1,0]
	v_pk_mul_f32 v[42:43], v[36:37], v[36:37]
	v_pk_mul_f32 v[44:45], v[34:35], v[34:35]
	v_pk_mul_f32 v[28:29], v[28:29], v[54:55] op_sel_hi:[1,0]
	v_pk_mov_b32 v[48:49], v[44:45], v[42:43] op_sel:[1,0]
	v_mov_b32_e32 v45, v43
	v_pk_add_f32 v[42:43], v[48:49], v[44:45]
	v_pk_mul_f32 v[44:45], v[32:33], v[32:33]
	v_pk_mul_f32 v[48:49], v[30:31], v[30:31]
	v_pk_add_f32 v[42:43], v[42:43], v[42:43] op_sel:[0,1] op_sel_hi:[1,0]
	v_pk_mov_b32 v[50:51], v[48:49], v[44:45] op_sel:[1,0]
	v_mov_b32_e32 v49, v45
	v_pk_add_f32 v[44:45], v[50:51], v[48:49]
	v_mul_f32_e32 v48, v10, v10
	v_mul_f32_e32 v49, v11, v11
	v_pk_add_f32 v[44:45], v[44:45], v[44:45] op_sel:[0,1] op_sel_hi:[1,0]
	v_mov_b32_e32 v43, v48
	v_mov_b32_e32 v45, v49
	v_pk_add_f32 v[42:43], v[42:43], v[44:45]
	v_mul_f32_e32 v44, v23, v23
	v_mul_f32_e32 v48, v25, v25
	v_mul_f32_e32 v50, v12, v12
	v_mul_f32_e32 v51, v13, v13
	v_pk_fma_f32 v[44:45], v[22:23], v[22:23], v[44:45] op_sel_hi:[1,1,0]
	v_pk_fma_f32 v[48:49], v[24:25], v[24:25], v[48:49] op_sel_hi:[1,1,0]
	v_mov_b32_e32 v45, v50
	v_mov_b32_e32 v49, v51
	v_pk_add_f32 v[44:45], v[44:45], v[48:49]
	v_pk_mul_f32 v[40:41], v[40:41], v[54:55] op_sel_hi:[1,0]
	v_pk_add_f32 v[42:43], v[42:43], v[44:45]
	v_pk_mul_f32 v[40:41], v[122:123], v[40:41]
	v_add_f32_e32 v42, v42, v43
	v_mov_b32_e32 v43, v42
	v_mov_b32_e32 v244, v42
	s_nop 1
	v_permlane16_swap_b32_e32 v43, v244
	v_add_f32_e32 v44, v244, v43
	v_mov_b32_e32 v45, v44
	v_mov_b32_e32 v244, v44
	v_pk_mul_f32 v[42:43], v[118:119], v[28:29]
	v_pk_mul_f32 v[28:29], v[120:121], v[26:27]
	v_cvt_pk_bf16_f32 v26, v38, v39
	v_cvt_pk_bf16_f32 v27, v40, v41
	s_nop 1
	v_permlane32_swap_b32_e32 v45, v244
	v_add_f32_e32 v38, v244, v45
	v_fmamk_f32 v38, v38, 0x3c800000, v180
	v_rsq_f32_e32 v38, v38
	v_cvt_pk_bf16_f32 v28, v28, v29
	v_cvt_pk_bf16_f32 v29, v42, v43
	global_store_dwordx4 v[46:47], v[26:29], off offset:64
	v_pk_mul_f32 v[30:31], v[30:31], v[38:39] op_sel_hi:[1,0]
	v_pk_mul_f32 v[32:33], v[32:33], v[38:39] op_sel_hi:[1,0]
	v_pk_mul_f32 v[26:27], v[34:35], v[38:39] op_sel_hi:[1,0]
	v_pk_mul_f32 v[28:29], v[36:37], v[38:39] op_sel_hi:[1,0]
	v_pk_mul_f32 v[26:27], v[156:157], v[26:27]
	v_pk_mul_f32 v[28:29], v[154:155], v[28:29]
	v_pk_mul_f32 v[30:31], v[128:129], v[30:31]
	v_cvt_pk_bf16_f32 v26, v26, v27
	v_cvt_pk_bf16_f32 v27, v28, v29
	v_pk_mul_f32 v[32:33], v[126:127], v[32:33]
	v_cvt_pk_bf16_f32 v28, v30, v31
	v_add_co_u32_e32 v30, vcc, s71, v152
	v_cvt_pk_bf16_f32 v29, v32, v33
	v_pk_mul_f32 v[22:23], v[22:23], v[38:39] op_sel_hi:[1,0]
	s_nop 0
	v_addc_co_u32_e32 v31, vcc, 0, v153, vcc
	global_store_dwordx4 v[30:31], v[26:29], off
	v_pk_mul_f32 v[22:23], v[124:125], v[22:23]
	v_pk_mul_f32 v[10:11], v[10:11], v[38:39] op_sel_hi:[1,0]
	v_pk_mul_f32 v[26:27], v[20:21], v[20:21]
	v_pk_mul_f32 v[28:29], v[18:19], v[18:19]
	v_pk_mul_f32 v[12:13], v[12:13], v[38:39] op_sel_hi:[1,0]
	v_pk_mov_b32 v[32:33], v[28:29], v[26:27] op_sel:[1,0]
	v_mov_b32_e32 v29, v27
	v_pk_add_f32 v[26:27], v[32:33], v[28:29]
	v_pk_mul_f32 v[28:29], v[16:17], v[16:17]
	v_pk_mul_f32 v[32:33], v[14:15], v[14:15]
	v_pk_add_f32 v[26:27], v[26:27], v[26:27] op_sel:[0,1] op_sel_hi:[1,0]
	v_pk_mov_b32 v[34:35], v[32:33], v[28:29] op_sel:[1,0]
	v_mov_b32_e32 v33, v29
	v_pk_add_f32 v[28:29], v[34:35], v[32:33]
	v_mul_f32_e32 v32, v2, v2
	v_mul_f32_e32 v33, v3, v3
	v_pk_add_f32 v[28:29], v[28:29], v[28:29] op_sel:[0,1] op_sel_hi:[1,0]
	v_mov_b32_e32 v27, v32
	v_mov_b32_e32 v29, v33
	v_pk_add_f32 v[26:27], v[26:27], v[28:29]
	v_mul_f32_e32 v28, v7, v7
	v_mul_f32_e32 v32, v9, v9
	v_mul_f32_e32 v34, v4, v4
	v_mul_f32_e32 v35, v5, v5
	v_pk_fma_f32 v[28:29], v[6:7], v[6:7], v[28:29] op_sel_hi:[1,1,0]
	v_pk_fma_f32 v[32:33], v[8:9], v[8:9], v[32:33] op_sel_hi:[1,1,0]
	v_mov_b32_e32 v29, v34
	v_mov_b32_e32 v33, v35
	v_pk_add_f32 v[28:29], v[28:29], v[32:33]
	v_pk_mul_f32 v[24:25], v[24:25], v[38:39] op_sel_hi:[1,0]
	v_pk_add_f32 v[26:27], v[26:27], v[28:29]
	v_pk_mul_f32 v[24:25], v[122:123], v[24:25]
	v_add_f32_e32 v26, v26, v27
	v_mov_b32_e32 v27, v26
	v_mov_b32_e32 v244, v26
	s_nop 1
	v_permlane16_swap_b32_e32 v27, v244
	v_add_f32_e32 v28, v244, v27
	v_mov_b32_e32 v29, v28
	v_mov_b32_e32 v244, v28
	v_pk_mul_f32 v[26:27], v[118:119], v[12:13]
	v_pk_mul_f32 v[12:13], v[120:121], v[10:11]
	v_cvt_pk_bf16_f32 v10, v22, v23
	v_cvt_pk_bf16_f32 v11, v24, v25
	s_nop 1
	v_permlane32_swap_b32_e32 v29, v244
	v_add_f32_e32 v22, v244, v29
	v_fmamk_f32 v22, v22, 0x3c800000, v180
	v_rsq_f32_e32 v22, v22
	v_cvt_pk_bf16_f32 v12, v12, v13
	v_cvt_pk_bf16_f32 v13, v26, v27
	global_store_dwordx4 v[30:31], v[10:13], off offset:64
	v_pk_mul_f32 v[14:15], v[14:15], v[22:23] op_sel_hi:[1,0]
	v_pk_mul_f32 v[16:17], v[16:17], v[22:23] op_sel_hi:[1,0]
	v_pk_mul_f32 v[10:11], v[18:19], v[22:23] op_sel_hi:[1,0]
	v_pk_mul_f32 v[12:13], v[20:21], v[22:23] op_sel_hi:[1,0]
	v_pk_mul_f32 v[10:11], v[156:157], v[10:11]
	v_pk_mul_f32 v[12:13], v[154:155], v[12:13]
	v_pk_mul_f32 v[14:15], v[128:129], v[14:15]
	v_cvt_pk_bf16_f32 v10, v10, v11
	v_cvt_pk_bf16_f32 v11, v12, v13
	v_pk_mul_f32 v[2:3], v[2:3], v[22:23] op_sel_hi:[1,0]
	v_cvt_pk_bf16_f32 v12, v14, v15
	v_add_co_u32_e32 v14, vcc, s72, v152
	v_pk_mul_f32 v[4:5], v[4:5], v[22:23] op_sel_hi:[1,0]
	s_nop 0
	v_addc_co_u32_e32 v15, vcc, 0, v153, vcc
	v_pk_mul_f32 v[16:17], v[126:127], v[16:17]
	v_pk_mul_f32 v[6:7], v[6:7], v[22:23] op_sel_hi:[1,0]
	v_cvt_pk_bf16_f32 v13, v16, v17
	global_store_dwordx4 v[14:15], v[10:13], off
	v_pk_mul_f32 v[8:9], v[8:9], v[22:23] op_sel_hi:[1,0]
	v_pk_mul_f32 v[6:7], v[124:125], v[6:7]
	v_pk_mul_f32 v[10:11], v[118:119], v[4:5]
	v_pk_mul_f32 v[4:5], v[120:121], v[2:3]
	v_pk_mul_f32 v[8:9], v[122:123], v[8:9]
	v_cvt_pk_bf16_f32 v2, v6, v7
	s_nop 0
	v_cvt_pk_bf16_f32 v3, v8, v9
	v_cvt_pk_bf16_f32 v4, v4, v5
	v_cvt_pk_bf16_f32 v5, v10, v11
	global_store_dwordx4 v[14:15], v[2:5], off offset:64
	s_andn2_b64 vcc, exec, s[4:5]
	s_mov_b64 s[4:5], -1
	s_cbranch_vccnz .LBB0_230
